# code placement: attention fast loop shifted by 4 bytes (other 8-byte phase)
# speedup vs baseline: 1.0068x; 1.0068x over previous
; #define LAS __attribute__((address_space(3)))
; #define AT_LOAD(K0, K1, V0, V1, T) do { const size_t e_ = (size_t)(128 * (T) + sr) * 64 + sc; \
;         K0 = *(const bf16x8*)(kcp + e_); V0 = *(const bf16x8*)(vcp + e_); K1 = *(const bf16x8*)(kcp + e_ + 64 * 64); V1 = *(const bf16x8*)(vcp + e_ + 64 * 64); } while (0)
; #define AT_STORE(K0, K1, V0, V1, BUF) do { *(LAS bf16x8*)(lds + AT_K + (BUF) * AT_KB + kst0) = K0; *(LAS bf16x8*)(lds + AT_K + (BUF) * AT_KB + kst1) = K1; \
;         *(LAS bf16x8*)(lds + AT_V + (BUF) * AT_VB + vst0) = V0; *(LAS bf16x8*)(lds + AT_V + (BUF) * AT_VB + vst1) = V1; } while (0)
; template <int VAR>
; __device__ __forceinline__ void attn_unit(const Args& a, int l, int b, int h, int qrow0  , bool ctxu, const bf16* Z, bf16* Y, LAS unsigned char* lds) {
;     ...
;     AT_LOAD(ka0, ka1, va0, va1, 0); AT_LOAD(kb0, kb1, vb0_, vb1_, 1); AT_STORE(ka0, ka1, va0, va1, 0);
;     const LAS unsigned char* Kb0 = lds + AT_K + comp * 64;
;     for (int t = 0; t < NT; t += 2) {
;         __syncthreads();
;         if (t + 2 < NT) AT_LOAD(ka0, ka1, va0, va1, t + 2);
;         attn_tile(Kb0, vb0, q0, q1, negm, m, o0, o1, lacc, t == 0, wsf, r32, hi);
.Lat_noprioF:
	s_waitcnt lgkmcnt(0)
	s_add_u32 m0, s51, 0x0
	s_nop 0
	global_load_lds_dwordx4 v158, s[36:37]
	s_add_u32 m0, s51, 0x2000
	s_nop 0
	global_load_lds_dwordx4 v159, s[36:37]
	s_add_u32 m0, s51, 0xc000
	s_nop 0
	global_load_lds_dwordx4 v160, s[48:49]
	s_add_u32 m0, s51, 0xe000
	s_nop 0
	global_load_lds_dwordx4 v161, s[48:49]
	s_add_u32 s36, s36, 0x4000
	s_addc_u32 s37, s37, 0
	s_add_u32 s48, s48, 0x4000
	s_addc_u32 s49, s49, 0
	s_add_u32 m0, s51, 0x4000
	s_nop 0
	global_load_lds_dwordx4 v158, s[36:37]
	s_add_u32 m0, s51, 0x6000
	s_nop 0
	global_load_lds_dwordx4 v159, s[36:37]
	s_add_u32 m0, s51, 0x10000
	s_nop 0
	global_load_lds_dwordx4 v160, s[48:49]
	s_add_u32 m0, s51, 0x12000
	s_nop 0
	global_load_lds_dwordx4 v161, s[48:49]
	s_add_u32 s36, s36, 0x4000
	s_addc_u32 s37, s37, 0
	s_add_u32 s48, s48, 0x4000
	s_addc_u32 s49, s49, 0
	s_waitcnt vmcnt(4)
	s_barrier
	s_add_u32 m0, s51, 0x8000
	s_nop 0
	global_load_lds_dwordx4 v158, s[36:37]
	s_add_u32 m0, s51, 0xa000
	s_nop 0
	global_load_lds_dwordx4 v159, s[36:37]
	s_add_u32 m0, s51, 0x14000
	s_nop 0
	global_load_lds_dwordx4 v160, s[48:49]
	s_add_u32 m0, s51, 0x16000
	s_nop 0
	global_load_lds_dwordx4 v161, s[48:49]
	s_add_u32 s36, s36, 0x4000
	s_addc_u32 s37, s37, 0
	s_add_u32 s48, s48, 0x4000
	s_addc_u32 s49, s49, 0
	ds_read_b128 v[48:51], v144 offset:0
	ds_read_b128 v[52:55], v145 offset:0
	ds_read_b128 v[56:59], v144 offset:4096
	ds_read_b128 v[60:63], v145 offset:4096
	s_nop 0
